# DA loop: loop counters and next-tile bias class computed inside PV gaps, rare/class/drain code moved out of line, running DMA addresses (fewer address ops per tile)
# speedup vs baseline: 1.0345x; 1.0099x over previous
; __device__ __forceinline__ void da_phase(LAS unsigned char* lds, const bf16* Q, const bf16* Kb, const bf16* Vb, bf16* O, const float* lq1, const float* lk1, const float* lq2, const float* lk2,
;                                          const float* t5, int G, int wave, int lane, int tid) {
;     ...
;         const int qrow0 = qb * 128 + 32 * w4;
;         H8 qf[4];
; #pragma unroll
;         for (int d0 = 0; d0 < 4; ++d0) qf[d0] = *(const GASP H8*)(Q + ((size_t)h * T + tok0 + qrow0 + r32) * 128 + comp * 64 + 16 * d0 + 8 * hi);
;         float m = 0.f, l = 0.f; F16 o[4];
; #pragma unroll
;         for (int db = 0; db < 4; ++db) o[db] = F16{};
;         int cur_cls = -1; float cb = 0.f, cbm = 0.f;
;         U4 pw[4] = {};
;         const int NT = S / 64;
;         const char* kub = (const char*)Kb + (((size_t)h * T + tok0 + 32 * (wave & 1)) * 128 + (wave >> 2) * 64 + ((wave >> 1) & 1) * 32) * 2;
;         const char* vub = (const char*)Vb + (((size_t)h * T + tok0 + 16 * ((2 * wave) & 3)) * 128 + ((2 * wave) >> 2) * 32) * 2;
;         const unsigned kofs = (unsigned)(((lane >> 2) * 128 + ((lane & 3) ^ ((lane >> 4) & 3)) * 8) * 2);
;         const unsigned vofs = (unsigned)(((lane >> 2) * 128 + (lane & 3) * 8) * 2);
;     ...
;         DA_DMA(0, 0, 0); DA_DMA(1, 1, 1);
;         int ks_cur = 0, ks_n2 = 2;
;         const unsigned kswz = (unsigned)((hi ^ ((r32 >> 2) & 3)) * 16);
;         const unsigned ka_base = ldsb + KS + comp * 8192 + r32 * 64;
;         S4 va[8], vb[8];
; #pragma unroll 1
;         for (int t = 0; t < NT; ++t) {
;             if (t + 1 < NT) asm volatile("s_waitcnt vmcnt(4)" ::: "memory"); else asm volatile("s_waitcnt vmcnt(0)" ::: "memory");
;             __builtin_amdgcn_s_barrier();
;             asm volatile("" ::: "memory");
;             const unsigned vaddr_p = ldsb + VS + ((t == 0 ? 0 : t + 3) & 3) * 16384 + vlane;
;             U4 kf[4];
;             const unsigned ka0 = ka_base + ks_cur * 16384 + kswz, ka1 = ka_base + ks_cur * 16384 + (kswz ^ 32u);
;             DS_RD128(kf[0], ka0, 0); DS_RD128(kf[1], ka1, 0); DS_RD128(kf[2], ka0, 4096); DS_RD128(kf[3], ka1, 4096);
;             DA_VREADS(va, vaddr_p, 0); DA_VREADS(vb, vaddr_p, 1);
;             const int kv0 = 64 * t; const int relmin = kv0 - (qrow0 + 31), relmax = kv0 + 63 - qrow0;
;             const int cls = 1 + (relmin >= 128 ? 1 : 0) - (relmax <= -128 ? 1 : 0);
.LBB0_201:
	s_lshl_b32 s18, s38, 7
	v_readlane_b32 s0, v254, 47
	s_or_b32 s38, s18, s0
	s_mul_i32 s10, s36, 0x18000
	s_add_u32 s0, s10, s38
	s_addc_u32 s1, 0, 0
	s_add_u32 s0, s0, s14
	s_addc_u32 s1, s1, s15
	v_lshl_add_u64 v[2:3], s[0:1], 0, v[188:189]
	v_readlane_b32 s0, v254, 20
	s_add_u32 s0, s14, s0
	s_addc_u32 s1, s15, 0
	s_add_u32 s0, s0, s10
	s_addc_u32 s1, s1, 0
	s_lshl_b64 s[0:1], s[0:1], 8
	v_lshlrev_b64 v[2:3], 8, v[2:3]
	s_add_u32 s10, s34, s0
	v_lshl_add_u64 v[2:3], v[192:193], 0, v[2:3]
	s_addc_u32 s11, s35, s1
	s_mov_b32 m0, s3
	global_load_dwordx4 v[120:123], v[2:3], off
	global_load_dwordx4 v[124:127], v[2:3], off offset:32
	global_load_dwordx4 v[128:131], v[2:3], off offset:64
	global_load_dwordx4 v[132:135], v[2:3], off offset:96
	s_add_u32 s16, s30, s0
	v_lshl_add_u64 v[2:3], s[10:11], 0, v[194:195]
	s_addc_u32 s17, s31, s1
	global_load_lds_dwordx4 v[2:3], off
	v_lshl_add_u64 v[4:5], v[2:3], 0, s[62:63]
	s_add_i32 m0, s3, 0x400
	s_mov_b64 s[10:11], 0x4000
	global_load_lds_dwordx4 v[4:5], off
	v_lshl_add_u64 v[4:5], s[16:17], 0, v[196:197]
	s_add_i32 m0, s3, 0xc000
	v_lshl_add_u64 v[6:7], v[4:5], 0, s[62:63]
	global_load_lds_dwordx4 v[4:5], off
	s_add_i32 m0, s3, 0xc400
	s_mov_b64 s[16:17], 0x5000
	global_load_lds_dwordx4 v[6:7], off
	v_lshl_add_u64 v[6:7], v[2:3], 0, s[10:11]
	s_add_i32 m0, s3, 0x4000
	v_lshl_add_u64 v[2:3], v[2:3], 0, s[16:17]
	global_load_lds_dwordx4 v[6:7], off
	s_add_i32 m0, s3, 0x4400
	v_add_u32_e32 v0, s18, v228
	global_load_lds_dwordx4 v[2:3], off
	v_lshl_add_u64 v[2:3], v[4:5], 0, s[10:11]
	s_add_i32 s10, 0, 0x10000
	v_readlane_b32 s11, v254, 22
	s_add_i32 m0, s10, s11
	v_readlane_b32 s11, v254, 23
	v_lshl_add_u64 v[2:3], v[4:5], 0, s[16:17]
	s_add_i32 m0, s10, s11
	v_mov_b32_e32 v14, v1
	v_mov_b32_e32 v15, v1
	v_lshl_add_u64 v[202:203], v[198:199], 0, s[0:1]
	v_lshl_add_u64 v[204:205], v[200:201], 0, s[0:1]
	v_sub_u32_e32 v231, v219, v0
	v_readlane_b32 s0, v254, 48
	v_mov_b32_e32 v0, v1
	v_mov_b32_e32 v2, v1
	v_mov_b32_e32 v3, v1
	v_mov_b32_e32 v4, v1
	v_mov_b32_e32 v5, v1
	v_mov_b32_e32 v6, v1
	v_mov_b32_e32 v7, v1
	v_mov_b32_e32 v8, v1
	v_mov_b32_e32 v9, v1
	v_mov_b32_e32 v10, v1
	v_mov_b32_e32 v11, v1
	v_mov_b32_e32 v12, v1
	v_mov_b32_e32 v13, v1
	v_mov_b64_e32 v[30:31], v[14:15]
	v_mov_b64_e32 v[46:47], v[14:15]
	v_mov_b64_e32 v[62:63], v[14:15]
	v_mov_b64_e32 v[78:79], v[14:15]
	v_subrev_u32_e32 v230, s18, v227
	s_sub_i32 s40, s0, s18
	s_lshl_b32 s41, s39, 6
	s_mov_b32 s44, 0
	s_mov_b32 s50, -1
	v_mov_b32_e32 v232, 0
	s_mov_b64 s[16:17], 0
	s_mov_b32 s45, 2
	v_mov_b32_e32 v112, 0
	v_mov_b32_e32 v113, 0
	v_mov_b32_e32 v114, 0
	v_mov_b32_e32 v115, 0
	v_mov_b32_e32 v116, 0
	v_mov_b32_e32 v117, 0
	v_mov_b32_e32 v118, 0
	v_mov_b32_e32 v119, 0
	v_mov_b32_e32 v136, 0
	v_mov_b32_e32 v137, 0
	v_mov_b32_e32 v138, 0
	v_mov_b32_e32 v139, 0
	v_mov_b32_e32 v140, 0
	v_mov_b32_e32 v141, 0
	v_mov_b32_e32 v142, 0
	v_mov_b32_e32 v143, 0
	v_mov_b64_e32 v[28:29], v[12:13]
	v_mov_b64_e32 v[26:27], v[10:11]
	v_mov_b64_e32 v[24:25], v[8:9]
	v_mov_b64_e32 v[22:23], v[6:7]
	v_mov_b64_e32 v[20:21], v[4:5]
	v_mov_b64_e32 v[18:19], v[2:3]
	v_mov_b64_e32 v[16:17], v[0:1]
	v_mov_b64_e32 v[44:45], v[12:13]
	v_mov_b64_e32 v[42:43], v[10:11]
	v_mov_b64_e32 v[40:41], v[8:9]
	v_mov_b64_e32 v[38:39], v[6:7]
	v_mov_b64_e32 v[36:37], v[4:5]
	v_mov_b64_e32 v[34:35], v[2:3]
	v_mov_b64_e32 v[32:33], v[0:1]
	v_mov_b64_e32 v[60:61], v[12:13]
	v_mov_b64_e32 v[58:59], v[10:11]
	v_mov_b64_e32 v[56:57], v[8:9]
	v_mov_b64_e32 v[54:55], v[6:7]
	v_mov_b64_e32 v[52:53], v[4:5]
	v_mov_b64_e32 v[50:51], v[2:3]
	v_mov_b64_e32 v[48:49], v[0:1]
	v_mov_b64_e32 v[76:77], v[12:13]
	v_mov_b64_e32 v[74:75], v[10:11]
	v_mov_b64_e32 v[72:73], v[8:9]
	v_mov_b64_e32 v[70:71], v[6:7]
	v_mov_b64_e32 v[68:69], v[4:5]
	v_mov_b64_e32 v[66:67], v[2:3]
	v_mov_b64_e32 v[64:65], v[0:1]
	v_mov_b32_e32 v229, 0
	v_mov_b32_e32 v233, 0
	v_mov_b32_e32 v14, 0
	s_mov_b32 s46, 0
	s_mov_b32 s47, 2
	s_waitcnt vmcnt(0)
	s_barrier
	s_add_i32 s0, s40, s44
	s_cmpk_gt_i32 s0, 0x9e
	s_cselect_b32 s20, 2, 1
	s_cmpk_lt_i32 s0, 0xff42
	s_cselect_b64 s[0:1], -1, 0
	s_cmp_lg_u64 s[0:1], 0
	s_subb_u32 s51, s20, 0
	s_mov_b64 s[0:1], 0x1b208000
	v_lshl_add_u64 v[204:205], v[204:205], 0, s[0:1]
	s_mov_b64 s[0:1], 0x27204000
	v_lshl_add_u64 v[202:203], v[202:203], 0, s[0:1]
	s_mov_b32 s18, 0xff800000
	s_mov_b32 s21, 0
	v_add_u32_e32 v253, v216, v191
	v_add_u32_e32 v252, v216, v218
	ds_read_b128 v[172:175], v253
	ds_read_b128 v[176:179], v252
	ds_read_b128 v[168:171], v253 offset:4096
	ds_read_b128 v[164:167], v252 offset:4096
	s_waitcnt lgkmcnt(0)
	v_mov_b32_e32 v0, 0
	v_mov_b32_e32 v2, 0
	v_mov_b32_e32 v3, 0
	v_mov_b32_e32 v5, 0
	v_mov_b32_e32 v6, 0
	v_mov_b32_e32 v7, 0
	v_mov_b32_e32 v8, 0
	v_mov_b32_e32 v9, 0
	v_mov_b32_e32 v10, 0
	v_mov_b32_e32 v15, 0
	v_mov_b32_e32 v80, 0
	v_mov_b32_e32 v81, 0
	v_mov_b32_e32 v82, 0
	v_mov_b32_e32 v83, 0
	v_mov_b32_e32 v84, 0
	v_mov_b32_e32 v85, 0
	v_mov_b32_e32 v86, 0
	v_mov_b32_e32 v87, 0
	v_mov_b32_e32 v108, 0
	v_mov_b32_e32 v109, 0
	v_mov_b32_e32 v110, 0
	v_mov_b32_e32 v111, 0
	v_mov_b32_e32 v144, 0
	v_mov_b32_e32 v145, 0
	v_mov_b32_e32 v146, 0
	v_mov_b32_e32 v147, 0
	v_mov_b32_e32 v156, 0
	v_mov_b32_e32 v157, 0
	v_mov_b32_e32 v158, 0
	v_mov_b32_e32 v159, 0
	v_mov_b32_e32 v160, 0
	v_mov_b32_e32 v161, 0
	s_branch .LBB0_204
.Lda_cls_change:
	s_cmp_gt_i32 s51, 1
	s_cbranch_scc0 .LBB0_211
	v_mov_b32_e32 v14, s93
	ds_read_b32 v233, v14
	s_cbranch_execz .LBB0_212
	s_branch .LBB0_214

; __device__ __forceinline__ int crow(int r, int hi) { return (r & 3) + 8 * (r >> 2) + 4 * hi; }
; __device__ __forceinline__ void da_phase(LAS unsigned char* lds, const bf16* Q, const bf16* Kb, const bf16* Vb, bf16* O, const float* lq1, const float* lk1, const float* lq2, const float* lk2,
;                                          const float* t5, int G, int wave, int lane, int tid) {
;     ...
;             if (t + 1 < NT) asm volatile("s_waitcnt vmcnt(4)" ::: "memory"); else asm volatile("s_waitcnt vmcnt(0)" ::: "memory");
;     ...
;             if (cls != cur_cls) { cur_cls = cls; cb = (cls == 2) ? lut[256] : ((cls == 0) ? lut[0] : 0.f); cbm = cb - m; }
;             F16 p0, p1;
;             {   typedef float F2i __attribute__((ext_vector_type(2))); F2i c2 = {cbm, cbm}; asm volatile("" : "+v"(c2));
; #pragma unroll
;                 for (int r = 0; r < 16; r += 2) { p0[r] = c2.x; p0[r + 1] = c2.y; p1[r] = c2.x; p1[r + 1] = c2.y; } }
;     ...
;             if (cls == 1) { const int base = kv0 - (qrow0 + r32) + 128;
; #pragma unroll
;                 for (int r = 0; r < 16; ++r) { const int i0 = base + crow(r, hi), i1 = i0 + 32;
;                     p0[r] += lut[min(max(i0, 0), 256)]; p1[r] += lut[min(max(i1, 0), 256)];
;                     if ((r & 1) == 1) asm volatile("" ::: "memory"); }
;                 a0 = __builtin_fmaxf(__builtin_fmaxf(p0[0], p0[1]), p0[2]);
; #pragma unroll
;                 for (int r = 3; r < 15; r += 2) a0 = __builtin_fmaxf(__builtin_fmaxf(a0, p0[r]), p0[r + 1]);
;                 a0 = __builtin_fmaxf(a0, p0[15]); }
.LBB0_214:
	s_waitcnt lgkmcnt(0)
	v_sub_f32_e32 v14, v233, v232
	v_mov_b32_e32 v236, v14
	v_mov_b32_e32 v237, v14
	v_mov_b32_e32 v238, v14
	v_mov_b32_e32 v239, v14
	v_mov_b32_e32 v240, v14
	v_mov_b32_e32 v241, v14
	v_mov_b32_e32 v242, v14
	v_mov_b32_e32 v243, v14
	v_mov_b32_e32 v244, v14
	v_mov_b32_e32 v245, v14
	v_mov_b32_e32 v246, v14
	v_mov_b32_e32 v247, v14
	v_mov_b32_e32 v248, v14
	v_mov_b32_e32 v249, v14
	v_mov_b32_e32 v250, v14
	v_mov_b32_e32 v251, v14
	s_mov_b32 s50, s51
	s_branch .LBB0_215
.Lda_cls1:
	v_add_u32_e32 v0, s44, v230
	v_add_u32_e32 v182, s44, v231
	v_add_u32_e32 v15, 0x80, v0
	v_add_u32_e32 v166, 0x81, v182
	v_med3_i32 v164, v15, 0, v210
	s_add_i32 s0, 0, 0x24000
	v_med3_i32 v165, v166, 0, v210
	v_lshl_add_u32 v164, v164, 2, s0
	v_lshl_add_u32 v165, v165, 2, s0
	v_max_i32_e32 v15, 0xffffffe0, v15
	ds_read_b32 v164, v164
	ds_read_b32 v165, v165
	v_max_i32_e32 v166, 0xffffffe0, v166
	v_add_u32_e32 v15, 32, v15
	v_add_u32_e32 v166, 32, v166
	v_min_u32_e32 v15, 0x100, v15
	v_min_u32_e32 v166, 0x100, v166
	v_lshl_add_u32 v15, v15, 2, s0
	v_lshl_add_u32 v166, v166, 2, s0
	ds_read_b32 v167, v166
	ds_read_b32 v166, v15
	v_add_u32_e32 v15, 0x82, v182
	v_add_u32_e32 v168, 0x83, v182
	s_waitcnt lgkmcnt(0)
	v_pk_add_f32 v[96:97], v[96:97], v[164:165]
	v_med3_i32 v164, v15, 0, v210
	v_med3_i32 v165, v168, 0, v210
	v_lshl_add_u32 v164, v164, 2, s0
	v_lshl_add_u32 v165, v165, 2, s0
	v_max_i32_e32 v15, 0xffffffe0, v15
	ds_read_b32 v164, v164
	ds_read_b32 v165, v165
	v_max_i32_e32 v168, 0xffffffe0, v168
	v_add_u32_e32 v15, 32, v15
	v_add_u32_e32 v168, 32, v168
	v_min_u32_e32 v15, 0x100, v15
	v_min_u32_e32 v168, 0x100, v168
	v_lshl_add_u32 v15, v15, 2, s0
	v_lshl_add_u32 v168, v168, 2, s0
	ds_read_b32 v169, v168
	ds_read_b32 v168, v15
	v_add_u32_e32 v15, 0x88, v182
	v_add_u32_e32 v170, 0x89, v182
	s_waitcnt lgkmcnt(0)
	v_pk_add_f32 v[98:99], v[98:99], v[164:165]
	v_med3_i32 v164, v15, 0, v210
	v_med3_i32 v165, v170, 0, v210
	v_lshl_add_u32 v164, v164, 2, s0
	v_lshl_add_u32 v165, v165, 2, s0
	v_max_i32_e32 v15, 0xffffffe0, v15
	ds_read_b32 v164, v164
	ds_read_b32 v165, v165
	v_max_i32_e32 v170, 0xffffffe0, v170
	v_add_u32_e32 v15, 32, v15
	v_add_u32_e32 v170, 32, v170
	v_min_u32_e32 v15, 0x100, v15
	v_min_u32_e32 v170, 0x100, v170
	v_lshl_add_u32 v15, v15, 2, s0
	v_lshl_add_u32 v170, v170, 2, s0
	ds_read_b32 v171, v170
	ds_read_b32 v170, v15
	v_add_u32_e32 v15, 0x8a, v182
	v_add_u32_e32 v172, 0x8b, v182
	s_waitcnt lgkmcnt(0)
	v_pk_add_f32 v[100:101], v[100:101], v[164:165]
	v_med3_i32 v164, v15, 0, v210
	v_med3_i32 v165, v172, 0, v210
	v_lshl_add_u32 v164, v164, 2, s0
	v_lshl_add_u32 v165, v165, 2, s0
	v_max_i32_e32 v15, 0xffffffe0, v15
	ds_read_b32 v164, v164
	ds_read_b32 v165, v165
	v_max_i32_e32 v172, 0xffffffe0, v172
	v_add_u32_e32 v15, 32, v15
	v_add_u32_e32 v172, 32, v172
	v_min_u32_e32 v15, 0x100, v15
	v_min_u32_e32 v172, 0x100, v172
	v_lshl_add_u32 v15, v15, 2, s0
	v_lshl_add_u32 v172, v172, 2, s0
	ds_read_b32 v173, v172
	ds_read_b32 v172, v15
	v_add_u32_e32 v15, 0x90, v182
	v_add_u32_e32 v174, 0x91, v182
	s_waitcnt lgkmcnt(0)
	v_pk_add_f32 v[102:103], v[102:103], v[164:165]
	v_med3_i32 v164, v15, 0, v210
	v_med3_i32 v165, v174, 0, v210
	v_lshl_add_u32 v164, v164, 2, s0
	v_lshl_add_u32 v165, v165, 2, s0
	v_max_i32_e32 v15, 0xffffffe0, v15
	ds_read_b32 v164, v164
	ds_read_b32 v165, v165
	v_max_i32_e32 v174, 0xffffffe0, v174
	v_add_u32_e32 v15, 32, v15
	v_add_u32_e32 v174, 32, v174
	v_min_u32_e32 v15, 0x100, v15
	v_min_u32_e32 v174, 0x100, v174
	v_lshl_add_u32 v15, v15, 2, s0
	v_lshl_add_u32 v174, v174, 2, s0
	ds_read_b32 v175, v174
	ds_read_b32 v174, v15
	v_add_u32_e32 v15, 0x92, v182
	v_add_u32_e32 v176, 0x93, v182
	s_waitcnt lgkmcnt(0)
	v_pk_add_f32 v[104:105], v[104:105], v[164:165]
	v_med3_i32 v164, v15, 0, v210
	v_med3_i32 v165, v176, 0, v210
	v_lshl_add_u32 v164, v164, 2, s0
	v_lshl_add_u32 v165, v165, 2, s0
	v_max_i32_e32 v15, 0xffffffe0, v15
	ds_read_b32 v164, v164
	ds_read_b32 v165, v165
	v_max_i32_e32 v176, 0xffffffe0, v176
	v_add_u32_e32 v15, 32, v15
	v_add_u32_e32 v176, 32, v176
	v_min_u32_e32 v15, 0x100, v15
	v_min_u32_e32 v176, 0x100, v176
	v_lshl_add_u32 v15, v15, 2, s0
	v_lshl_add_u32 v176, v176, 2, s0
	ds_read_b32 v177, v176
	ds_read_b32 v176, v15
	v_add_u32_e32 v15, 0x98, v182
	v_add_u32_e32 v178, 0x99, v182
	s_waitcnt lgkmcnt(0)
	v_pk_add_f32 v[106:107], v[106:107], v[164:165]
	v_med3_i32 v164, v15, 0, v210
	v_med3_i32 v165, v178, 0, v210
	v_lshl_add_u32 v164, v164, 2, s0
	v_lshl_add_u32 v165, v165, 2, s0
	ds_read_b32 v164, v164
	ds_read_b32 v165, v165
	v_max_i32_e32 v15, 0xffffffe0, v15
	v_max_i32_e32 v178, 0xffffffe0, v178
	v_add_u32_e32 v15, 32, v15
	v_add_u32_e32 v178, 32, v178
	v_min_u32_e32 v15, 0x100, v15
	v_min_u32_e32 v178, 0x100, v178
	v_lshl_add_u32 v15, v15, 2, s0
	v_lshl_add_u32 v178, v178, 2, s0
	v_add_u32_e32 v0, 0x9b, v0
	ds_read_b32 v179, v178
	ds_read_b32 v178, v15
	s_waitcnt lgkmcnt(0)
	v_pk_add_f32 v[108:109], v[108:109], v[164:165]
	v_add_u32_e32 v15, 0x9a, v182
	v_med3_i32 v165, v0, 0, v210
	v_max_i32_e32 v0, 0xffffffe0, v0
	v_med3_i32 v164, v15, 0, v210
	v_max_i32_e32 v15, 0xffffffe0, v15
	v_add_u32_e32 v0, 32, v0
	v_add_u32_e32 v15, 32, v15
	v_min_u32_e32 v0, 0x100, v0
	v_lshl_add_u32 v164, v164, 2, s0
	v_min_u32_e32 v15, 0x100, v15
	v_lshl_add_u32 v165, v165, 2, s0
	v_lshl_add_u32 v0, v0, 2, s0
	v_lshl_add_u32 v15, v15, 2, s0
	ds_read_b32 v164, v164
	ds_read_b32 v165, v165
	ds_read_b32 v183, v0
	ds_read_b32 v182, v15
	v_max_f32_e32 v0, v96, v97
	v_max3_f32 v0, v0, v98, v99
	v_max3_f32 v0, v0, v100, v101
	v_max3_f32 v0, v0, v102, v103
	v_max3_f32 v0, v0, v104, v105
	v_max3_f32 v0, v0, v106, v107
	s_waitcnt lgkmcnt(0)
	v_pk_add_f32 v[110:111], v[110:111], v[164:165]
	v_max3_f32 v0, v0, v108, v109
	v_pk_add_f32 v[80:81], v[80:81], v[166:167]
	v_pk_add_f32 v[82:83], v[82:83], v[168:169]
	v_pk_add_f32 v[84:85], v[84:85], v[170:171]
	v_pk_add_f32 v[86:87], v[86:87], v[172:173]
	v_pk_add_f32 v[88:89], v[88:89], v[174:175]
	v_pk_add_f32 v[90:91], v[90:91], v[176:177]
	v_pk_add_f32 v[92:93], v[92:93], v[178:179]
	v_pk_add_f32 v[94:95], v[94:95], v[182:183]
	v_max3_f32 v0, v0, v110, v111
	s_branch .LBB0_221
.Lda_mid_v0:
	s_waitcnt vmcnt(0)
	s_branch .Lda_mid_bar

; #define LGKM_WAIT(n) asm volatile("s_waitcnt lgkmcnt(" #n ")" ::: "memory")
; #define SCHED_FENCE() __builtin_amdgcn_sched_barrier(0)
; #define DA_VREADS(v, vaddr, DB) do { _Pragma("unroll") for (int k_ = 0; k_ < 4; ++k_) { DS_RDTR(v[2 * k_], vaddr, (DB) * 4096 + k_ * 1024); DS_RDTR(v[2 * k_ + 1], vaddr, (DB) * 4096 + k_ * 1024 + 512); } } while (0)
; #define DA_GROUP(v, DB, P, B, acc) do { DA_GAP(v, DB, 0, P, (B), acc); DA_GAP(v, DB, 1, P, (B) + 2, acc); DA_GAP(v, DB, 2, P, (B) + 4, acc); DA_GAP(v, DB, 3, P, (B) + 6, acc); } while (0)
; #define DA_PACK8(P, B) (U4){cvtpk(P[(B)], P[(B) + 1]), cvtpk(P[(B) + 2], P[(B) + 3]), cvtpk(P[(B) + 4], P[(B) + 5]), cvtpk(P[(B) + 6], P[(B) + 7])}
; __device__ __forceinline__ void da_phase(LAS unsigned char* lds, const bf16* Q, const bf16* Kb, const bf16* Vb, bf16* O, const float* lq1, const float* lk1, const float* lq2, const float* lk2,
;                                          const float* t5, int G, int wave, int lane, int tid) {
;     ...
;         for (int t = 0; t < NT; ++t) {
;             if (t + 1 < NT) asm volatile("s_waitcnt vmcnt(4)" ::: "memory"); else asm volatile("s_waitcnt vmcnt(0)" ::: "memory");
;             __builtin_amdgcn_s_barrier();
;     ...
;             const int kv0 = 64 * t; const int relmin = kv0 - (qrow0 + 31), relmax = kv0 + 63 - qrow0;
;             const int cls = 1 + (relmin >= 128 ? 1 : 0) - (relmax <= -128 ? 1 : 0);
;     ...
;             float sa = 0.f, sb = 0.f;
;             SCHED_FENCE(); DA_GROUP(va, 0, p0, 0, sa);
;             DA_VREADS(va, vaddr_p, 2); SCHED_FENCE();
;             DA_GROUP(vb, 1, p0, 8, sa);
;             DA_VREADS(vb, vaddr_p, 3); LGKM_WAIT(8); SCHED_FENCE();
;             DA_GROUP(va, 2, p1, 0, sa);
;             LGKM_WAIT(0); SCHED_FENCE();
;             DA_GROUP(vb, 3, p1, 8, sa);
;             l += sa + sb;
;             pw[0] = DA_PACK8(p0, 0); pw[1] = DA_PACK8(p0, 8); pw[2] = DA_PACK8(p1, 0); pw[3] = DA_PACK8(p1, 8);
;             ks_cur = (ks_cur == 2) ? 0 : ks_cur + 1; ks_n2 = (ks_n2 == 2) ? 0 : ks_n2 + 1;
.LBB0_203:
	s_cmp_ge_u32 s45, s39
	s_cbranch_scc1 .Lda_mid_v0
	s_waitcnt vmcnt(4)
.Lda_mid_bar:
	s_barrier
	v_mfma_f32_32x32x16_bf16 v[64:79], v[140:143], v[160:163], v[64:79]
	v_exp_f32_e32 v0, v96
	v_exp_f32_e32 v15, v97
	s_add_i32 s0, s46, 1
	v_add_f32_e32 v96, v15, v0
	s_cmp_lg_u32 s46, 2
	s_cselect_b32 s46, s0, 0
	v_lshl_add_u32 v252, s46, 14, v216
	v_add_u32_e32 v253, v252, v191
	v_add_u32_e32 v252, v252, v218
	v_mfma_f32_32x32x16_bf16 v[64:79], v[136:139], v[156:159], v[64:79]
	v_exp_f32_e32 v156, v98
	v_exp_f32_e32 v157, v99
	v_add_f32_e32 v96, v156, v96
	v_add_f32_e32 v96, v157, v96
	ds_read_b128 v[172:175], v253
	ds_read_b128 v[176:179], v252
	ds_read_b128 v[168:171], v253 offset:4096
	ds_read_b128 v[164:167], v252 offset:4096
	v_mfma_f32_32x32x16_bf16 v[64:79], v[116:119], v[152:155], v[64:79]
	v_exp_f32_e32 v158, v100
	v_exp_f32_e32 v159, v101
	v_add_f32_e32 v96, v158, v96
	v_add_f32_e32 v96, v159, v96
	s_add_i32 s0, s47, 1
	s_cmp_lg_u32 s47, 2
	s_cselect_b32 s47, s0, 0
	s_and_b32 s21, s16, 0xc000
	v_mfma_f32_32x32x16_bf16 v[64:79], v[112:115], v[148:151], v[64:79]
	v_exp_f32_e32 v160, v102
	v_exp_f32_e32 v161, v103
	v_add_f32_e32 v162, v160, v96
	ds_read_b64_tr_b16 v[96:97], v234 offset:8192
	ds_read_b64_tr_b16 v[98:99], v234 offset:8704
	ds_read_b64_tr_b16 v[100:101], v234 offset:9216
	ds_read_b64_tr_b16 v[102:103], v234 offset:9728
	ds_read_b64_tr_b16 v[148:149], v234 offset:10240
	ds_read_b64_tr_b16 v[150:151], v234 offset:10752
	ds_read_b64_tr_b16 v[152:153], v234 offset:11264
	ds_read_b64_tr_b16 v[154:155], v234 offset:11776
	v_add_f32_e32 v162, v161, v162
	v_mfma_f32_32x32x16_bf16 v[48:63], v[140:143], v[144:147], v[48:63]
	v_exp_f32_e32 v144, v104
	v_exp_f32_e32 v145, v105
	v_add_f32_e32 v104, v144, v162
	v_add_f32_e32 v104, v145, v104
	s_add_u32 s16, s16, 0x4000
	s_addc_u32 s17, s17, 0
	s_add_i32 s45, s45, 1
	s_add_i32 s44, s44, 64
	v_mfma_f32_32x32x16_bf16 v[48:63], v[136:139], v[10:13], v[48:63]
	v_exp_f32_e32 v146, v106
	v_exp_f32_e32 v147, v107
	v_add_f32_e32 v10, v146, v104
	v_add_f32_e32 v10, v147, v10
	s_add_i32 s0, s40, s44
	s_cmpk_gt_i32 s0, 0x9e
	s_cselect_b32 s20, 2, 1
	v_mfma_f32_32x32x16_bf16 v[48:63], v[116:119], v[6:9], v[48:63]
	v_exp_f32_e32 v108, v108
	v_exp_f32_e32 v109, v109
	v_add_f32_e32 v6, v108, v10
	v_add_f32_e32 v6, v109, v6
	s_cmpk_lt_i32 s0, 0xff42
	s_cselect_b64 s[0:1], -1, 0
	s_cmp_lg_u64 s[0:1], 0
	s_subb_u32 s51, s20, 0
	v_mfma_f32_32x32x16_bf16 v[48:63], v[112:115], v[2:5], v[48:63]
	v_exp_f32_e32 v110, v110
	v_exp_f32_e32 v111, v111
	v_add_f32_e32 v162, v110, v6
	ds_read_b64_tr_b16 v[2:3], v234 offset:12288
	ds_read_b64_tr_b16 v[4:5], v234 offset:12800
	ds_read_b64_tr_b16 v[6:7], v234 offset:13312
	ds_read_b64_tr_b16 v[8:9], v234 offset:13824
	ds_read_b64_tr_b16 v[10:11], v234 offset:14336
	ds_read_b64_tr_b16 v[12:13], v234 offset:14848
	ds_read_b64_tr_b16 v[104:105], v234 offset:15360
	ds_read_b64_tr_b16 v[106:107], v234 offset:15872
	s_waitcnt lgkmcnt(8)
	v_add_f32_e32 v162, v111, v162
	v_mfma_f32_32x32x16_bf16 v[32:47], v[140:143], v[96:99], v[32:47]
	v_exp_f32_e32 v80, v80
	v_exp_f32_e32 v81, v81
	v_add_f32_e32 v96, v80, v162
	v_add_f32_e32 v96, v81, v96
	v_mfma_f32_32x32x16_bf16 v[32:47], v[136:139], v[100:103], v[32:47]
	v_exp_f32_e32 v82, v82
	v_exp_f32_e32 v83, v83
	v_add_f32_e32 v96, v82, v96
	v_add_f32_e32 v96, v83, v96
	v_mfma_f32_32x32x16_bf16 v[32:47], v[116:119], v[148:151], v[32:47]
	v_exp_f32_e32 v84, v84
	v_exp_f32_e32 v85, v85
	v_add_f32_e32 v96, v84, v96
	v_add_f32_e32 v96, v85, v96
	v_mfma_f32_32x32x16_bf16 v[32:47], v[112:115], v[152:155], v[32:47]
	v_exp_f32_e32 v86, v86
	v_exp_f32_e32 v87, v87
	v_add_f32_e32 v96, v86, v96
	v_add_f32_e32 v96, v87, v96
	s_waitcnt lgkmcnt(0)
	v_mfma_f32_32x32x16_bf16 v[16:31], v[140:143], v[2:5], v[16:31]
	v_exp_f32_e32 v2, v88
	v_exp_f32_e32 v3, v89
	v_add_f32_e32 v4, v2, v96
	v_add_f32_e32 v4, v3, v4
	v_mfma_f32_32x32x16_bf16 v[16:31], v[136:139], v[6:9], v[16:31]
	v_exp_f32_e32 v5, v90
	v_exp_f32_e32 v6, v91
	v_add_f32_e32 v4, v5, v4
	v_add_f32_e32 v4, v6, v4
	v_mfma_f32_32x32x16_bf16 v[16:31], v[116:119], v[10:13], v[16:31]
	v_exp_f32_e32 v7, v92
	v_exp_f32_e32 v8, v93
	v_add_f32_e32 v4, v7, v4
	v_add_f32_e32 v4, v8, v4
	v_mfma_f32_32x32x16_bf16 v[16:31], v[112:115], v[104:107], v[16:31]
	v_exp_f32_e32 v9, v94
	v_exp_f32_e32 v10, v95
	v_add_f32_e32 v4, v9, v4
	v_add_f32_e32 v4, v10, v4
	v_add_f32_e32 v229, v229, v4
	s_cmp_eq_u32 s41, s44
	s_cbranch_scc1 .LBB0_228
; __device__ __forceinline__ void da_phase(LAS unsigned char* lds, const bf16* Q, const bf16* Kb, const bf16* Vb, bf16* O, const float* lq1, const float* lk1, const float* lq2, const float* lk2,
;                                          const float* t5, int G, int wave, int lane, int tid) {
;     ...
;             const unsigned vaddr_p = ldsb + VS + ((t == 0 ? 0 : t + 3) & 3) * 16384 + vlane;
;             U4 kf[4];
;             const unsigned ka0 = ka_base + ks_cur * 16384 + kswz, ka1 = ka_base + ks_cur * 16384 + (kswz ^ 32u);
;             DS_RD128(kf[0], ka0, 0); DS_RD128(kf[1], ka1, 0); DS_RD128(kf[2], ka0, 4096); DS_RD128(kf[3], ka1, 4096);
;             DA_VREADS(va, vaddr_p, 0); DA_VREADS(vb, vaddr_p, 1);
;             const int kv0 = 64 * t; const int relmin = kv0 - (qrow0 + 31), relmax = kv0 + 63 - qrow0;
;             const int cls = 1 + (relmin >= 128 ? 1 : 0) - (relmax <= -128 ? 1 : 0);
;             if (cls != cur_cls) { cur_cls = cls; cb = (cls == 2) ? lut[256] : ((cls == 0) ? lut[0] : 0.f); cbm = cb - m; }
;             F16 p0, p1;
;             {   typedef float F2i __attribute__((ext_vector_type(2))); F2i c2 = {cbm, cbm}; asm volatile("" : "+v"(c2));
; #pragma unroll
;                 for (int r = 0; r < 16; r += 2) { p0[r] = c2.x; p0[r + 1] = c2.y; p1[r] = c2.x; p1[r + 1] = c2.y; } }
;             asm volatile("s_waitcnt lgkmcnt(15)" ::: "memory"); SCHED_FENCE();
; #pragma unroll
;             for (int d0 = 0; d0 < 4; ++d0) p0 = __builtin_amdgcn_mfma_f32_32x32x16_bf16(__builtin_bit_cast(H8, kf[d0]), qf[d0], p0, 0, 0, 0);
;             SCHED_FENCE();
;             DS_RD128(kf[0], ka0, 2048); DS_RD128(kf[1], ka1, 2048); DS_RD128(kf[2], ka0, 6144); DS_RD128(kf[3], ka1, 6144);
;             if (t + 2 < NT) DA_DMA_K(t + 2, ks_n2);
;             LGKM_WAIT(0); SCHED_FENCE();
;             float a0;
;             p1 = __builtin_amdgcn_mfma_f32_32x32x16_bf16(__builtin_bit_cast(H8, kf[0]), qf[0], p1, 0, 0, 0); a0 = __builtin_fmaxf(__builtin_fmaxf(p0[0], p0[1]), p0[2]); a0 = __builtin_fmaxf(__builtin_fmaxf(a0, p0[3]), p0[4]); asm volatile("" : "+v"(a0)); SCHED_FENCE();
;             p1 = __builtin_amdgcn_mfma_f32_32x32x16_bf16(__builtin_bit_cast(H8, kf[1]), qf[1], p1, 0, 0, 0); a0 = __builtin_fmaxf(__builtin_fmaxf(a0, p0[5]), p0[6]); a0 = __builtin_fmaxf(__builtin_fmaxf(a0, p0[7]), p0[8]); asm volatile("" : "+v"(a0)); SCHED_FENCE();
.LBB0_204:
	v_add_u32_e32 v234, s21, v217
	s_cmp_eq_u32 s51, s50
	s_cbranch_scc0 .Lda_cls_change
.LBB0_215:
	v_cvt_pk_bf16_f32 v138, v108, v109
	v_cvt_pk_bf16_f32 v139, v110, v111
	v_mfma_f32_32x32x16_bf16 v[96:111], v[172:175], v[120:123], v[236:251]
	v_cvt_pk_bf16_f32 v140, v0, v15
	v_cvt_pk_bf16_f32 v141, v156, v157
	v_cvt_pk_bf16_f32 v142, v158, v159
	v_cvt_pk_bf16_f32 v143, v160, v161
	v_cvt_pk_bf16_f32 v136, v144, v145
	v_cvt_pk_bf16_f32 v137, v146, v147
	ds_read_b64_tr_b16 v[160:161], v234 offset:0
	ds_read_b64_tr_b16 v[162:163], v234 offset:512
	ds_read_b64_tr_b16 v[156:157], v234 offset:1024
	ds_read_b64_tr_b16 v[158:159], v234 offset:1536
	v_mfma_f32_32x32x16_bf16 v[96:111], v[176:179], v[124:127], v[96:111]
	v_cvt_pk_bf16_f32 v116, v80, v81
	v_cvt_pk_bf16_f32 v117, v82, v83
	v_cvt_pk_bf16_f32 v118, v84, v85
	v_cvt_pk_bf16_f32 v119, v86, v87
	ds_read_b64_tr_b16 v[152:153], v234 offset:2048
	ds_read_b64_tr_b16 v[154:155], v234 offset:2560
	ds_read_b64_tr_b16 v[148:149], v234 offset:3072
	ds_read_b64_tr_b16 v[150:151], v234 offset:3584
	v_mfma_f32_32x32x16_bf16 v[96:111], v[168:171], v[128:131], v[96:111]
	v_cvt_pk_bf16_f32 v112, v2, v3
	v_cvt_pk_bf16_f32 v113, v5, v6
	v_cvt_pk_bf16_f32 v114, v7, v8
	v_cvt_pk_bf16_f32 v115, v9, v10
	ds_read_b64_tr_b16 v[144:145], v234 offset:4096
	ds_read_b64_tr_b16 v[146:147], v234 offset:4608
	ds_read_b64_tr_b16 v[10:11], v234 offset:5120
	ds_read_b64_tr_b16 v[12:13], v234 offset:5632
	v_mfma_f32_32x32x16_bf16 v[96:111], v[164:167], v[132:135], v[96:111]
	ds_read_b64_tr_b16 v[6:7], v234 offset:6144
	ds_read_b64_tr_b16 v[8:9], v234 offset:6656
	ds_read_b64_tr_b16 v[2:3], v234 offset:7168
	ds_read_b64_tr_b16 v[4:5], v234 offset:7680
	ds_read_b128 v[176:179], v253 offset:2048
	ds_read_b128 v[172:175], v252 offset:2048
	ds_read_b128 v[168:171], v253 offset:6144
	ds_read_b128 v[164:167], v252 offset:6144
	s_cmp_ge_u32 s45, s39
	s_cbranch_scc1 .LBB0_217
	s_lshl_b32 s0, s47, 14
	s_add_i32 m0, s3, s0
	v_lshl_add_u64 v[182:183], v[204:205], 0, s[62:63]
	global_load_lds_dwordx4 v[204:205], off
	s_add_i32 m0, m0, 0x400
	s_mov_b64 s[0:1], 0x4000
	v_lshl_add_u64 v[204:205], v[204:205], 0, s[0:1]
	global_load_lds_dwordx4 v[182:183], off
.LBB0_217:
	s_waitcnt lgkmcnt(0)
	v_mfma_f32_32x32x16_bf16 v[80:95], v[176:179], v[120:123], v[236:251]
	v_max3_f32 v0, v96, v97, v98
	v_max3_f32 v0, v0, v99, v100
	v_mfma_f32_32x32x16_bf16 v[80:95], v[172:175], v[124:127], v[80:95]
	v_max3_f32 v0, v0, v101, v102
	v_max3_f32 v0, v0, v103, v104
	v_mfma_f32_32x32x16_bf16 v[80:95], v[168:171], v[128:131], v[80:95]
	v_max3_f32 v0, v0, v105, v106
	v_max3_f32 v0, v0, v107, v108
	v_mfma_f32_32x32x16_bf16 v[80:95], v[164:167], v[132:135], v[80:95]
	v_max_f32_e32 v0, v0, v0
	v_max_f32_e32 v15, v109, v109
	v_max_f32_e32 v0, v0, v15
	v_max3_f32 v0, v0, v110, v111
	s_cmp_gt_u32 s45, s39
	s_cbranch_scc1 .Lda_vskip
	s_add_i32 s0, s16, 0x4000
	s_and_b32 s0, s0, 0xc000
	s_add_i32 s20, s3, s0
	s_add_i32 m0, s20, 0xc000
	v_lshl_add_u64 v[164:165], v[202:203], 0, s[62:63]
	global_load_lds_dwordx4 v[202:203], off
	s_add_i32 m0, m0, 0x400
	s_mov_b64 s[0:1], 0x4000
	v_lshl_add_u64 v[202:203], v[202:203], 0, s[0:1]
	global_load_lds_dwordx4 v[164:165], off
.LBB0_219:
	s_cmp_eq_u32 s51, 1
	s_cbranch_scc1 .Lda_cls1
